# ret+mamba scan units: state image (ST) written before the first barrier, second workgroup barrier per unit removed
# speedup vs baseline: 1.0079x; 1.0079x over previous
; __device__ __forceinline__ unsigned cvt_pk_bf16(float lo, float hi) { unsigned r; asm("v_cvt_pk_bf16_f32 %0, %1, %2" : "=v"(r) : "v"(lo), "v"(hi)); return r; }
; template <int DK, int DV, bool SEPQ> ...
;     ...
;     for (int ct = 0; ct < NCTW; ++ct)
; #pragma unroll
;         for (int vt = 0; vt < NVT; ++vt) { const f32x4 s = S[ct][vt]; u32x2 w; w.x = cvt_pk_bf16(s[0], s[1]); w.y = cvt_pk_bf16(s[2], s[3]);
;             *(u32x2*)(ST + (16 * vt + fr) * LQ + 16 * (wid * NCTW + ct) + 4 * fq) = w; }
;     __syncthreads();
; __device__ __forceinline__ void ret_block(ArgsP a_, unsigned char* smem) { const ArgsP a = a_;
;     ...
; #pragma unroll
;         for (int e = 0; e < 4; ++e) { const int idx = tid + 512 * e, i = idx >> 5, cc = idx & 31; *(u32x4*)(QA + i * LQ + 8 * cc) = qpre[e]; *(u32x4*)(KB + i * LQ + 8 * cc) = kpre[e]; }
;         *(u32x4*)(VT + vv * LJ + 8 * jg) = (u32x4){(unsigned)vpre[0] | ((unsigned)vpre[1] << 16), (unsigned)vpre[2] | ((unsigned)vpre[3] << 16), (unsigned)vpre[4] | ((unsigned)vpre[5] << 16), (unsigned)vpre[6] | ((unsigned)vpre[7] << 16)};
;         if (tid < 64) { GI[tid] = (float)((tid + 1 < len) ? tid + 1 : len) * lgam; DECJ[tid] = tid < len ? __expf((float)(len - 1 - tid) * lgam) : 0.f; }
;         if (tid < 256) SDEC[tid] = __expf((float)len * lgam);
;         __syncthreads();
.LBB0_263:
	s_or_b64 exec, exec, s[64:65]
	s_waitcnt vmcnt(0)
	v_cvt_pk_bf16_f32 v0, v40, v41
	v_cvt_pk_bf16_f32 v1, v42, v43
	v_cvt_pk_bf16_f32 v2, v56, v57
	v_cvt_pk_bf16_f32 v3, v58, v59
	ds_write2_b64 v143, v[0:1], v[2:3] offset1:4
	v_cvt_pk_bf16_f32 v4, v44, v45
	v_cvt_pk_bf16_f32 v5, v46, v47
	v_cvt_pk_bf16_f32 v6, v60, v61
	v_cvt_pk_bf16_f32 v7, v62, v63
	v_add_u32_e32 v9, 0x2000, v143
	ds_write2_b64 v9, v[4:5], v[6:7] offset0:32 offset1:36
	v_cvt_pk_bf16_f32 v0, v48, v49
	v_cvt_pk_bf16_f32 v1, v50, v51
	v_cvt_pk_bf16_f32 v2, v64, v65
	v_cvt_pk_bf16_f32 v3, v66, v67
	v_add_u32_e32 v8, 0x4000, v143
	ds_write2_b64 v8, v[0:1], v[2:3] offset0:64 offset1:68
	v_cvt_pk_bf16_f32 v4, v52, v53
	v_cvt_pk_bf16_f32 v5, v54, v55
	v_cvt_pk_bf16_f32 v6, v68, v69
	v_cvt_pk_bf16_f32 v7, v70, v71
	v_add_u32_e32 v9, 0x6000, v143
	ds_write2_b64 v9, v[4:5], v[6:7] offset0:96 offset1:100
	s_cmp_ge_i32 s86, s79
	s_waitcnt vmcnt(0) lgkmcnt(0)
	s_barrier
	s_cbranch_scc1 .LBB0_269
	s_cmp_ge_i32 s92, s77
	s_mov_b64 s[64:65], -1
	s_cbranch_scc0 .LBB0_266
	s_sub_i32 s64, s92, s77
	s_mul_i32 s64, s64, s13
	s_add_i32 s70, s64, s78
	s_ashr_i32 s64, s70, 2
	s_and_b32 s64, s64, -8
	s_add_i32 s67, s64, 0x4080
	s_mov_b64 s[64:65], 0

; template <int DK, int DV, bool SEPQ> ...
;     ...
;     {
;         const float gi_i = GI[16 * m + fr];
;         const int n0 = 2 * hw, n1 = 2 * hw + 1; const bool do0 = n0 <= m, do1 = n1 <= m;
;         f32x4 acc0 = {0.f, 0.f, 0.f, 0.f}, acc1 = {0.f, 0.f, 0.f, 0.f};
; #pragma unroll
;         for (int vt = 0; vt < NVTW; ++vt) O[vt] = (f32x4){0.f, 0.f, 0.f, 0.f};
; #pragma unroll
;         for (int ks = 0; ks < DK / 32; ++ks) {
;             const bf16x8 qf = *(const bf16x8*)(QA + (16 * m + fr) * LQ + 32 * ks + 8 * fq);
;             if (do0) { const bf16x8 kf = *(const bf16x8*)(KB + (16 * n0 + fr) * LQ + 32 * ks + 8 * fq); acc0 = __builtin_amdgcn_mfma_f32_16x16x32_bf16(kf, qf, acc0, 0, 0, 0); }
;             if (do1) { const bf16x8 kf = *(const bf16x8*)(KB + (16 * n1 + fr) * LQ + 32 * ks + 8 * fq); acc1 = __builtin_amdgcn_mfma_f32_16x16x32_bf16(kf, qf, acc1, 0, 0, 0); }
;             bf16x8 qs = qf; if (SEPQ) qs = *(const bf16x8*)(QS + (16 * m + fr) * LQ + 32 * ks + 8 * fq);
; #pragma unroll
; __device__ __forceinline__ void ret_block(ArgsP a_, unsigned char* smem) { const ArgsP a = a_;
;     ...
;         { const int cp = tid & 127, jq = tid >> 7;
;           float dj[16];
; #pragma unroll
;           for (int q4 = 0; q4 < 4; ++q4) { const f32x4 t = *(const f32x4*)(DECJ + 16 * jq + 4 * q4); dj[4 * q4] = t[0]; dj[4 * q4 + 1] = t[1]; dj[4 * q4 + 2] = t[2]; dj[4 * q4 + 3] = t[3]; }
;           unsigned lo[8], hi[8];
; #pragma unroll
;           for (int e = 0; e < 8; ++e) { const int j = 16 * jq + 2 * e; const unsigned w0 = *(const unsigned*)(KB + j * LQ + 2 * cp), w1 = *(const unsigned*)(KB + (j + 1) * LQ + 2 * cp);
;               lo[e] = cvt_pk_bf16(__uint_as_float(w0 << 16) * dj[2 * e], __uint_as_float(w1 << 16) * dj[2 * e + 1]);
;               hi[e] = cvt_pk_bf16(__uint_as_float(w0 & 0xffff0000u) * dj[2 * e], __uint_as_float(w1 & 0xffff0000u) * dj[2 * e + 1]); }
;           *(u32x4*)(KT + (2 * cp) * LJ + 16 * jq) = (u32x4){lo[0], lo[1], lo[2], lo[3]}; *(u32x4*)(KT + (2 * cp) * LJ + 16 * jq + 8) = (u32x4){lo[4], lo[5], lo[6], lo[7]};
;           *(u32x4*)(KT + (2 * cp + 1) * LJ + 16 * jq) = (u32x4){hi[0], hi[1], hi[2], hi[3]}; *(u32x4*)(KT + (2 * cp + 1) * LJ + 16 * jq + 8) = (u32x4){hi[4], hi[5], hi[6], hi[7]}; }
.LBB0_269:
	ds_read_b128 v[214:217], v142
	ds_read_b128 v[218:221], v142 offset:16
	ds_read_b128 v[222:225], v142 offset:32
	ds_read_b128 v[226:229], v142 offset:48
	ds_read_b32 v230, v140 offset:33792
	ds_read_b32 v231, v141 offset:34320
	ds_read_b32 v232, v140 offset:34848
	ds_read_b32 v233, v141 offset:35376
	ds_read_b32 v234, v140 offset:35904
	ds_read_b32 v235, v141 offset:36432
	ds_read_b32 v236, v140 offset:36960
	ds_read_b32 v237, v141 offset:37488
	ds_read_b32 v238, v140 offset:38016
	ds_read_b32 v239, v141 offset:38544
	ds_read_b32 v240, v140 offset:39072
	s_waitcnt lgkmcnt(10)
	v_lshlrev_b32_e32 v19, 16, v230
	ds_read_b32 v241, v141 offset:39600
	ds_read_b32 v242, v140 offset:40128
	ds_read_b32 v243, v141 offset:40656
	ds_read_b32 v244, v140 offset:41184
	ds_read_b32 v245, v141 offset:41712
	s_waitcnt lgkmcnt(14)
	v_lshlrev_b32_e32 v80, 16, v231
	v_and_b32_e32 v16, 0xffff0000, v230
	v_and_b32_e32 v18, 0xffff0000, v231
	v_mul_f32_e32 v16, v214, v16
	v_mul_f32_e32 v18, v215, v18
	v_mul_f32_e32 v19, v214, v19
	v_cvt_pk_bf16_f32 v72, v16, v18
	v_mul_f32_e32 v80, v215, v80
	v_cvt_pk_bf16_f32 v80, v19, v80
	s_waitcnt lgkmcnt(13)
	v_lshlrev_b32_e32 v19, 16, v232
	s_waitcnt lgkmcnt(12)
	v_lshlrev_b32_e32 v73, 16, v233
	v_and_b32_e32 v16, 0xffff0000, v232
	v_and_b32_e32 v18, 0xffff0000, v233
	v_mul_f32_e32 v73, v217, v73
	v_mul_f32_e32 v16, v216, v16
	v_mul_f32_e32 v18, v217, v18
	v_mul_f32_e32 v19, v216, v19
	v_cvt_pk_bf16_f32 v81, v19, v73
	v_cvt_pk_bf16_f32 v73, v16, v18
	s_waitcnt lgkmcnt(11)
	v_lshlrev_b32_e32 v19, 16, v234
	s_waitcnt lgkmcnt(10)
	v_lshlrev_b32_e32 v74, 16, v235
	v_and_b32_e32 v16, 0xffff0000, v234
	v_and_b32_e32 v18, 0xffff0000, v235
	v_mul_f32_e32 v74, v219, v74
	v_mul_f32_e32 v16, v218, v16
	v_mul_f32_e32 v18, v219, v18
	v_mul_f32_e32 v19, v218, v19
	v_cvt_pk_bf16_f32 v82, v19, v74
	v_cvt_pk_bf16_f32 v74, v16, v18
	s_waitcnt lgkmcnt(9)
	v_lshlrev_b32_e32 v19, 16, v236
	s_waitcnt lgkmcnt(8)
	v_lshlrev_b32_e32 v75, 16, v237
	v_and_b32_e32 v16, 0xffff0000, v236
	v_and_b32_e32 v18, 0xffff0000, v237
	v_mul_f32_e32 v75, v221, v75
	v_mul_f32_e32 v16, v220, v16
	v_mul_f32_e32 v18, v221, v18
	v_mul_f32_e32 v19, v220, v19
	v_cvt_pk_bf16_f32 v83, v19, v75
	v_cvt_pk_bf16_f32 v75, v16, v18
	s_waitcnt lgkmcnt(7)
	v_lshlrev_b32_e32 v19, 16, v238
	s_waitcnt lgkmcnt(6)
	v_lshlrev_b32_e32 v88, 16, v239
	v_and_b32_e32 v16, 0xffff0000, v238
	v_and_b32_e32 v18, 0xffff0000, v239
	v_mul_f32_e32 v16, v222, v16
	v_mul_f32_e32 v18, v223, v18
	v_mul_f32_e32 v19, v222, v19
	v_cvt_pk_bf16_f32 v84, v16, v18
	v_mul_f32_e32 v88, v223, v88
	v_cvt_pk_bf16_f32 v88, v19, v88
	s_waitcnt lgkmcnt(5)
	v_lshlrev_b32_e32 v19, 16, v240
	s_waitcnt lgkmcnt(4)
	v_lshlrev_b32_e32 v85, 16, v241
	v_and_b32_e32 v16, 0xffff0000, v240
	v_and_b32_e32 v18, 0xffff0000, v241
	v_mul_f32_e32 v85, v225, v85
	v_mul_f32_e32 v16, v224, v16
	v_mul_f32_e32 v18, v225, v18
	v_mul_f32_e32 v19, v224, v19
	v_cvt_pk_bf16_f32 v89, v19, v85
	v_cvt_pk_bf16_f32 v85, v16, v18
	s_waitcnt lgkmcnt(3)
	v_lshlrev_b32_e32 v19, 16, v242
	s_waitcnt lgkmcnt(2)
	v_lshlrev_b32_e32 v86, 16, v243
	v_and_b32_e32 v16, 0xffff0000, v242
	v_and_b32_e32 v18, 0xffff0000, v243
	v_mul_f32_e32 v86, v227, v86
	v_mul_f32_e32 v16, v226, v16
	v_mul_f32_e32 v18, v227, v18
	v_mul_f32_e32 v19, v226, v19
	v_cvt_pk_bf16_f32 v90, v19, v86
	v_cvt_pk_bf16_f32 v86, v16, v18
	s_waitcnt lgkmcnt(1)
	v_lshlrev_b32_e32 v19, 16, v244
	s_waitcnt lgkmcnt(0)
	v_lshlrev_b32_e32 v76, 16, v245
	v_and_b32_e32 v16, 0xffff0000, v244
	v_and_b32_e32 v18, 0xffff0000, v245
	v_mul_f32_e32 v19, v228, v19
	v_mul_f32_e32 v16, v228, v16
	v_mul_f32_e32 v18, v229, v18
	v_mul_f32_e32 v76, v229, v76
	v_cvt_pk_bf16_f32 v91, v19, v76
	v_cvt_pk_bf16_f32 v87, v16, v18
	ds_write_b128 v124, v[80:83]
	ds_write_b128 v124, v[88:91] offset:16
	ds_write_b128 v124, v[72:75] offset:144
	ds_write_b128 v124, v[84:87] offset:160
	s_waitcnt lgkmcnt(0)
	ds_read_b32 v92, v125
	ds_read_b128 v[214:217], v126
	ds_read_b128 v[218:221], v127 offset:33792
	ds_read_b128 v[222:225], v127 offset:42240
	ds_read_b128 v[226:229], v165
	ds_read_b128 v[230:233], v165 offset:8448
	ds_read_b128 v[166:169], v126 offset:64
	ds_read_b128 v[170:173], v127 offset:33856
	ds_read_b128 v[174:177], v127 offset:42304
	ds_read_b128 v[178:181], v165 offset:64
	ds_read_b128 v[182:185], v165 offset:8512
	s_waitcnt lgkmcnt(5)
	v_mfma_f32_16x16x32_bf16 v[76:79], v[218:221], v[214:217], 0
	v_mfma_f32_16x16x32_bf16 v[72:75], v[222:225], v[214:217], 0
	v_mfma_f32_16x16x32_bf16 v[80:83], v[226:229], v[214:217], 0
	v_mfma_f32_16x16x32_bf16 v[84:87], v[230:233], v[214:217], 0
	ds_read_b128 v[214:217], v126 offset:128
	ds_read_b128 v[218:221], v127 offset:33920
	ds_read_b128 v[222:225], v127 offset:42368
	ds_read_b128 v[226:229], v165 offset:128
	ds_read_b128 v[230:233], v165 offset:8576
	s_waitcnt lgkmcnt(5)
	v_mfma_f32_16x16x32_bf16 v[76:79], v[170:173], v[166:169], v[76:79]
	v_mfma_f32_16x16x32_bf16 v[72:75], v[174:177], v[166:169], v[72:75]
	v_mfma_f32_16x16x32_bf16 v[80:83], v[178:181], v[166:169], v[80:83]
	v_mfma_f32_16x16x32_bf16 v[84:87], v[182:185], v[166:169], v[84:87]
	ds_read_b128 v[166:169], v126 offset:192
	ds_read_b128 v[170:173], v127 offset:33984
	ds_read_b128 v[174:177], v127 offset:42432
	ds_read_b128 v[178:181], v165 offset:192
	ds_read_b128 v[182:185], v165 offset:8640
	s_waitcnt lgkmcnt(5)
	v_mfma_f32_16x16x32_bf16 v[76:79], v[218:221], v[214:217], v[76:79]
	v_mfma_f32_16x16x32_bf16 v[72:75], v[222:225], v[214:217], v[72:75]
	v_mfma_f32_16x16x32_bf16 v[80:83], v[226:229], v[214:217], v[80:83]
	v_mfma_f32_16x16x32_bf16 v[84:87], v[230:233], v[214:217], v[84:87]
	ds_read_b128 v[214:217], v126 offset:256
	ds_read_b128 v[218:221], v127 offset:34048
	ds_read_b128 v[222:225], v127 offset:42496
	ds_read_b128 v[226:229], v165 offset:256
	ds_read_b128 v[230:233], v165 offset:8704
	s_waitcnt lgkmcnt(5)
; __device__ __forceinline__ unsigned cvt_pk_bf16(float lo, float hi) { unsigned r; asm("v_cvt_pk_bf16_f32 %0, %1, %2" : "=v"(r) : "v"(lo), "v"(hi)); return r; }
; template <int DK, int DV, bool SEPQ> ...
;     ...
;         for (int ks = 0; ks < DK / 32; ++ks) {
;             const bf16x8 qf = *(const bf16x8*)(QA + (16 * m + fr) * LQ + 32 * ks + 8 * fq);
;             if (do0) { const bf16x8 kf = *(const bf16x8*)(KB + (16 * n0 + fr) * LQ + 32 * ks + 8 * fq); acc0 = __builtin_amdgcn_mfma_f32_16x16x32_bf16(kf, qf, acc0, 0, 0, 0); }
;             if (do1) { const bf16x8 kf = *(const bf16x8*)(KB + (16 * n1 + fr) * LQ + 32 * ks + 8 * fq); acc1 = __builtin_amdgcn_mfma_f32_16x16x32_bf16(kf, qf, acc1, 0, 0, 0); }
;             bf16x8 qs = qf; if (SEPQ) qs = *(const bf16x8*)(QS + (16 * m + fr) * LQ + 32 * ks + 8 * fq);
; #pragma unroll
;             for (int vt = 0; vt < NVTW; ++vt) { const bf16x8 sf = *(const bf16x8*)(ST + (16 * (hw * NVTW + vt) + fr) * LQ + 32 * ks + 8 * fq); O[vt] = __builtin_amdgcn_mfma_f32_16x16x32_bf16(sf, qs, O[vt], 0, 0, 0); }
;         }
; #pragma unroll
;         for (int nn = 0; nn < 2; ++nn) {
;             const int n = 2 * hw + nn; const f32x4 acc = nn == 0 ? acc0 : acc1;
;             const f32x4 gj = *(const f32x4*)(GI + 16 * n + 4 * fq); const int i = 16 * m + fr, j0 = 16 * n + 4 * fq; float p[4];
; #pragma unroll
;             for (int e = 0; e < 4; ++e) p[e] = (j0 + e <= i) ? acc[e] * __expf(gi_i - gj[e]) : 0.f;
;             u32x2 w; w.x = cvt_pk_bf16(p[0], p[1]); w.y = cvt_pk_bf16(p[2], p[3]); *(u32x2*)(P + (16 * m + fr) * LJ + j0) = w;
;         }
;         const float ei = __expf(gi_i);
; #pragma unroll
;         for (int vt = 0; vt < NVTW; ++vt) O[vt] = O[vt] * ei;
;     }
;     __syncthreads();
	v_mfma_f32_16x16x32_bf16 v[76:79], v[170:173], v[166:169], v[76:79]
	v_mfma_f32_16x16x32_bf16 v[72:75], v[174:177], v[166:169], v[72:75]
	v_mfma_f32_16x16x32_bf16 v[80:83], v[178:181], v[166:169], v[80:83]
	v_mfma_f32_16x16x32_bf16 v[84:87], v[182:185], v[166:169], v[84:87]
	ds_read_b128 v[166:169], v126 offset:320
	ds_read_b128 v[170:173], v127 offset:34112
	ds_read_b128 v[174:177], v127 offset:42560
	ds_read_b128 v[178:181], v165 offset:320
	ds_read_b128 v[182:185], v165 offset:8768
	s_waitcnt lgkmcnt(5)
	v_mfma_f32_16x16x32_bf16 v[76:79], v[218:221], v[214:217], v[76:79]
	v_mfma_f32_16x16x32_bf16 v[72:75], v[222:225], v[214:217], v[72:75]
	v_mfma_f32_16x16x32_bf16 v[80:83], v[226:229], v[214:217], v[80:83]
	v_mfma_f32_16x16x32_bf16 v[84:87], v[230:233], v[214:217], v[84:87]
	ds_read_b128 v[214:217], v126 offset:384
	ds_read_b128 v[218:221], v127 offset:34176
	ds_read_b128 v[222:225], v127 offset:42624
	ds_read_b128 v[226:229], v165 offset:384
	ds_read_b128 v[230:233], v165 offset:8832
	s_waitcnt lgkmcnt(5)
	v_mfma_f32_16x16x32_bf16 v[76:79], v[170:173], v[166:169], v[76:79]
	v_mfma_f32_16x16x32_bf16 v[72:75], v[174:177], v[166:169], v[72:75]
	v_mfma_f32_16x16x32_bf16 v[80:83], v[178:181], v[166:169], v[80:83]
	v_mfma_f32_16x16x32_bf16 v[84:87], v[182:185], v[166:169], v[84:87]
	ds_read_b128 v[166:169], v126 offset:448
	ds_read_b128 v[170:173], v127 offset:34240
	ds_read_b128 v[174:177], v127 offset:42688
	ds_read_b128 v[178:181], v165 offset:448
	ds_read_b128 v[182:185], v165 offset:8896
	s_waitcnt lgkmcnt(5)
	v_mfma_f32_16x16x32_bf16 v[76:79], v[218:221], v[214:217], v[76:79]
	v_mfma_f32_16x16x32_bf16 v[72:75], v[222:225], v[214:217], v[72:75]
	v_mfma_f32_16x16x32_bf16 v[80:83], v[226:229], v[214:217], v[80:83]
	v_mfma_f32_16x16x32_bf16 v[84:87], v[230:233], v[214:217], v[84:87]
	s_waitcnt lgkmcnt(0)
	v_mfma_f32_16x16x32_bf16 v[76:79], v[170:173], v[166:169], v[76:79]
	v_mfma_f32_16x16x32_bf16 v[72:75], v[174:177], v[166:169], v[72:75]
	v_mfma_f32_16x16x32_bf16 v[80:83], v[178:181], v[166:169], v[80:83]
	v_mfma_f32_16x16x32_bf16 v[84:87], v[182:185], v[166:169], v[84:87]
	s_nop 7
	v_cmp_gt_i32_e32 vcc, s89, v132
	ds_read_b128 v[88:91], v128
	s_waitcnt lgkmcnt(0)
	v_sub_f32_e32 v16, v92, v88
	v_mul_f32_e32 v16, 0x3fb8aa3b, v16
	v_exp_f32_e32 v16, v16
	v_sub_f32_e32 v18, v92, v89
	v_sub_f32_e32 v19, v92, v90
	v_mul_f32_e32 v18, 0x3fb8aa3b, v18
	v_mul_f32_e32 v16, v76, v16
	v_mul_f32_e32 v19, 0x3fb8aa3b, v19
	v_sub_f32_e32 v76, v92, v91
	v_exp_f32_e32 v18, v18
	v_exp_f32_e32 v19, v19
	v_mul_f32_e32 v76, 0x3fb8aa3b, v76
	v_exp_f32_e32 v76, v76
	v_mul_f32_e32 v18, v77, v18
	v_mul_f32_e32 v19, v78, v19
	v_cndmask_b32_e64 v18, 0, v18, s[50:51]
	v_cndmask_b32_e64 v19, v19, 0, s[52:53]
	v_mul_f32_e32 v76, v79, v76
	v_cndmask_b32_e64 v16, v16, 0, s[48:49]
	v_cndmask_b32_e64 v76, v76, 0, s[54:55]
	v_cvt_pk_bf16_f32 v18, v16, v18
	v_cvt_pk_bf16_f32 v19, v19, v76
	ds_write_b64 v129, v[18:19]
	ds_read_b128 v[76:79], v128 offset:64
	s_waitcnt lgkmcnt(0)
	v_sub_f32_e32 v16, v92, v76
	v_mul_f32_e32 v16, 0x3fb8aa3b, v16
	v_sub_f32_e32 v18, v92, v77
	v_exp_f32_e32 v16, v16
	v_mul_f32_e32 v18, 0x3fb8aa3b, v18
	v_exp_f32_e32 v18, v18
	v_sub_f32_e32 v19, v92, v78
	v_mul_f32_e32 v16, v72, v16
	v_sub_f32_e32 v72, v92, v79
	v_mul_f32_e32 v18, v73, v18
	v_mul_f32_e32 v19, 0x3fb8aa3b, v19
	v_mul_f32_e32 v72, 0x3fb8aa3b, v72
	v_cndmask_b32_e64 v16, v16, 0, s[56:57]
	v_cndmask_b32_e64 v18, 0, v18, s[58:59]
	v_exp_f32_e32 v19, v19
	v_exp_f32_e32 v72, v72
	v_cvt_pk_bf16_f32 v18, v16, v18
	v_mul_f32_e32 v16, 0x3fb8aa3b, v92
	v_exp_f32_e32 v16, v16
	v_mul_f32_e32 v19, v74, v19
	v_mul_f32_e32 v72, v75, v72
	v_cndmask_b32_e64 v19, v19, 0, s[60:61]
	v_cndmask_b32_e64 v72, v72, 0, s[62:63]
	v_cvt_pk_bf16_f32 v19, v19, v72
	ds_write_b64 v129, v[18:19] offset:32
	v_pk_mul_f32 v[72:73], v[16:17], v[80:81] op_sel_hi:[0,1]
	v_pk_mul_f32 v[74:75], v[16:17], v[82:83] op_sel_hi:[0,1]
	v_pk_mul_f32 v[76:77], v[16:17], v[84:85] op_sel_hi:[0,1]
	v_pk_mul_f32 v[78:79], v[16:17], v[86:87] op_sel_hi:[0,1]
	s_waitcnt lgkmcnt(0)
	s_barrier
; __device__ __forceinline__ unsigned cvt_pk_bf16(float lo, float hi) { unsigned r; asm("v_cvt_pk_bf16_f32 %0, %1, %2" : "=v"(r) : "v"(lo), "v"(hi)); return r; }
; template <int DK, int DV, bool SEPQ> ...
;     ...
; #pragma unroll
;     for (int ks = 0; ks < 2; ++ks) { const bf16x8 pf = *(const bf16x8*)(P + (16 * m + fr) * LJ + 32 * ks + 8 * fq);
; #pragma unroll
;         for (int vt = 0; vt < NVTW; ++vt) { const bf16x8 vf = *(const bf16x8*)(VT + (16 * (hw * NVTW + vt) + fr) * LJ + 32 * ks + 8 * fq); O[vt] = __builtin_amdgcn_mfma_f32_16x16x32_bf16(vf, pf, O[vt], 0, 0, 0); } }
; #pragma unroll
;     for (int ct = 0; ct < NCTW; ++ct) { const int ctg = wid * NCTW + ct; const f32x4 dec = *(const f32x4*)(SDEC + 16 * ctg + 4 * fq);
; #pragma unroll
;         for (int vt = 0; vt < NVT; ++vt) S[ct][vt] = S[ct][vt] * dec;
; #pragma unroll
;         for (int ks = 0; ks < 2; ++ks) { const bf16x8 kf = *(const bf16x8*)(KT + (16 * ctg + fr) * LJ + 32 * ks + 8 * fq);
; #pragma unroll
;             for (int vt = 0; vt < NVT; ++vt) { const bf16x8 vf = *(const bf16x8*)(VT2 + (16 * vt + fr) * LJ + 32 * ks + 8 * fq); S[ct][vt] = __builtin_amdgcn_mfma_f32_16x16x32_bf16(kf, vf, S[ct][vt], 0, 0, 0); } } }
; __device__ __forceinline__ void ret_block(ArgsP a_, unsigned char* smem) { const ArgsP a = a_;
;     ...
;         const int m = wid >> 1, hw = wid & 1, i = 16 * m + fr;
;         if (i < len) {
; #pragma unroll
;             for (int vt = 0; vt < 2; ++vt) *(u32x2*)(OB + (size_t)(row0 + i) * 2048 + h * 512 + vs * 64 + 16 * (hw * 2 + vt) + 4 * fq) = (u32x2){cvt_pk_bf16(O[vt][0], O[vt][1]), cvt_pk_bf16(O[vt][2], O[vt][3])}; }
	ds_read_b128 v[214:217], v130
	ds_read_b128 v[218:221], v144
	ds_read_b128 v[222:225], v144 offset:2304
	ds_read_b128 v[226:229], v130 offset:64
	ds_read_b128 v[230:233], v144 offset:64
	ds_read_b128 v[234:237], v144 offset:2368
	ds_read_b128 v[238:241], v131
	ds_read_b128 v[242:245], v145
	ds_read_b128 v[246:249], v147
	ds_read_b128 v[166:169], v147 offset:2304
	ds_read_b128 v[170:173], v147 offset:4608
	ds_read_b128 v[174:177], v147 offset:6912
	ds_read_b128 v[178:181], v145 offset:64
	ds_read_b128 v[182:185], v147 offset:64
	ds_read_b128 v[80:83], v147 offset:2368
	s_waitcnt lgkmcnt(13)
	v_mfma_f32_16x16x32_bf16 v[72:75], v[218:221], v[214:217], v[72:75]
	ds_read_b128 v[84:87], v147 offset:4672
	ds_read_b128 v[88:91], v147 offset:6976
	s_waitcnt lgkmcnt(14)
	v_mfma_f32_16x16x32_bf16 v[76:79], v[222:225], v[214:217], v[76:79]
	ds_read_b128 v[218:221], v131 offset:64
	s_waitcnt lgkmcnt(13)
	v_mfma_f32_16x16x32_bf16 v[72:75], v[230:233], v[226:229], v[72:75]
	ds_read_b128 v[214:217], v164
	ds_read_b128 v[222:225], v164 offset:64
	s_waitcnt lgkmcnt(14)
	v_mfma_f32_16x16x32_bf16 v[76:79], v[234:237], v[226:229], v[76:79]
	s_waitcnt lgkmcnt(13)
	v_pk_mul_f32 v[42:43], v[42:43], v[240:241]
	v_pk_mul_f32 v[40:41], v[40:41], v[238:239]
	v_pk_mul_f32 v[46:47], v[46:47], v[240:241]
	v_pk_mul_f32 v[44:45], v[44:45], v[238:239]
	v_pk_mul_f32 v[50:51], v[50:51], v[240:241]
	v_pk_mul_f32 v[48:49], v[48:49], v[238:239]
	v_pk_mul_f32 v[54:55], v[54:55], v[240:241]
	v_pk_mul_f32 v[52:53], v[52:53], v[238:239]
	s_waitcnt lgkmcnt(11)
	v_mfma_f32_16x16x32_bf16 v[40:43], v[242:245], v[246:249], v[40:43]
	s_waitcnt lgkmcnt(10)
	v_mfma_f32_16x16x32_bf16 v[44:47], v[242:245], v[166:169], v[44:47]
	s_waitcnt lgkmcnt(9)
	v_mfma_f32_16x16x32_bf16 v[48:51], v[242:245], v[170:173], v[48:51]
	s_waitcnt lgkmcnt(8)
	v_mfma_f32_16x16x32_bf16 v[52:55], v[242:245], v[174:177], v[52:55]
	s_waitcnt lgkmcnt(6)
	v_mfma_f32_16x16x32_bf16 v[40:43], v[178:181], v[182:185], v[40:43]
	s_waitcnt lgkmcnt(5)
	v_mfma_f32_16x16x32_bf16 v[44:47], v[178:181], v[80:83], v[44:47]
	s_waitcnt lgkmcnt(4)
	v_mfma_f32_16x16x32_bf16 v[48:51], v[178:181], v[84:87], v[48:51]
	s_waitcnt lgkmcnt(3)
	v_mfma_f32_16x16x32_bf16 v[52:55], v[178:181], v[88:91], v[52:55]
	s_waitcnt lgkmcnt(2)
	v_pk_mul_f32 v[58:59], v[58:59], v[220:221]
	v_pk_mul_f32 v[56:57], v[56:57], v[218:219]
	v_pk_mul_f32 v[62:63], v[62:63], v[220:221]
	v_pk_mul_f32 v[60:61], v[60:61], v[218:219]
	v_pk_mul_f32 v[66:67], v[66:67], v[220:221]
	v_pk_mul_f32 v[64:65], v[64:65], v[218:219]
	v_pk_mul_f32 v[70:71], v[70:71], v[220:221]
	v_pk_mul_f32 v[68:69], v[68:69], v[218:219]
	s_waitcnt lgkmcnt(1)
	v_mfma_f32_16x16x32_bf16 v[56:59], v[214:217], v[246:249], v[56:59]
	v_mfma_f32_16x16x32_bf16 v[60:63], v[214:217], v[166:169], v[60:63]
	v_mfma_f32_16x16x32_bf16 v[64:67], v[214:217], v[170:173], v[64:67]
	v_mfma_f32_16x16x32_bf16 v[68:71], v[214:217], v[174:177], v[68:71]
	s_waitcnt lgkmcnt(0)
	v_mfma_f32_16x16x32_bf16 v[56:59], v[222:225], v[182:185], v[56:59]
	v_mfma_f32_16x16x32_bf16 v[60:63], v[222:225], v[80:83], v[60:63]
	v_mfma_f32_16x16x32_bf16 v[64:67], v[222:225], v[84:87], v[64:67]
	v_mfma_f32_16x16x32_bf16 v[68:71], v[222:225], v[88:91], v[68:71]
	s_and_saveexec_b64 s[64:65], vcc
	s_cbranch_execz .LBB0_303
	v_add_u32_e32 v18, s88, v132
	v_ashrrev_i32_e32 v19, 31, v18
	v_lshlrev_b64 v[18:19], 12, v[18:19]
	v_lshl_add_u64 v[18:19], s[26:27], 0, v[18:19]
	s_lshl_b32 s70, s91, 10
	s_mov_b32 s71, s12
	v_lshl_add_u64 v[18:19], v[18:19], 0, s[70:71]
	s_lshl_b32 s70, s90, 7
	v_lshl_add_u64 v[18:19], v[18:19], 0, s[70:71]
	v_mov_b32_e32 v113, v17
	v_lshl_add_u64 v[18:19], v[18:19], 0, v[112:113]
	v_mov_b32_e32 v115, v17
	v_cvt_pk_bf16_f32 v72, v72, v73
	v_cvt_pk_bf16_f32 v73, v74, v75
	v_lshl_add_u64 v[18:19], v[18:19], 0, v[114:115]
	global_store_dwordx2 v[18:19], v[72:73], off
	v_cvt_pk_bf16_f32 v72, v76, v77
	v_cvt_pk_bf16_f32 v73, v78, v79
	global_store_dwordx2 v[18:19], v[72:73], off offset:32

; __device__ __forceinline__ unsigned cvt_pk_bf16(float lo, float hi) { unsigned r; asm("v_cvt_pk_bf16_f32 %0, %1, %2" : "=v"(r) : "v"(lo), "v"(hi)); return r; }
; __device__ __forceinline__ float bf2f(bf16_t b) { return __uint_as_float(((unsigned)b) << 16); }
; template <int DK, int DV, bool SEPQ> ...
;     ...
;     for (int ct = 0; ct < NCTW; ++ct)
; #pragma unroll
;         for (int vt = 0; vt < NVT; ++vt) { const f32x4 s = S[ct][vt]; u32x2 w; w.x = cvt_pk_bf16(s[0], s[1]); w.y = cvt_pk_bf16(s[2], s[3]);
;             *(u32x2*)(ST + (16 * vt + fr) * LQ + 16 * (wid * NCTW + ct) + 4 * fq) = w; }
;     __syncthreads();
; __device__ __forceinline__ void mamba_block(ArgsP a_, unsigned char* smem) { const ArgsP a = a_;
;     ...
;         { unsigned w1[4], w2[4];
; #pragma unroll
;           for (int e = 0; e < 4; ++e) { const int j = 8 * jg + 2 * e; const float x0 = bf2f(xpre[2 * e]), x1 = bf2f(xpre[2 * e + 1]);
;               w1[e] = cvt_pk_bf16(x0 * DTV[j], x1 * DTV[j + 1]); w2[e] = cvt_pk_bf16(x0 * W2[j], x1 * W2[j + 1]); }
;           *(u32x4*)(VT + vv * LJ + 8 * jg) = (u32x4){w1[0], w1[1], w1[2], w1[3]}; *(u32x4*)(VT2 + vv * LJ + 8 * jg) = (u32x4){w2[0], w2[1], w2[2], w2[3]}; }
;         { const int cp = tid & 63, jq = tid >> 6;
;           unsigned lo[4], hi[4];
; #pragma unroll
;           for (int e = 0; e < 4; ++e) { const int j = 8 * jq + 2 * e; const unsigned w0 = *(const unsigned*)(KB + j * LQ + 2 * cp), w1 = *(const unsigned*)(KB + (j + 1) * LQ + 2 * cp);
;               lo[e] = (w0 & 0xffffu) | (w1 << 16); hi[e] = (w0 >> 16) | (w1 & 0xffff0000u); }
;           *(u32x4*)(KT + (2 * cp) * LJ + 8 * jq) = (u32x4){lo[0], lo[1], lo[2], lo[3]}; *(u32x4*)(KT + (2 * cp + 1) * LJ + 8 * jq) = (u32x4){hi[0], hi[1], hi[2], hi[3]}; }
.LBB0_348:
	s_or_b64 exec, exec, s[74:75]
	s_waitcnt vmcnt(0)
	v_cvt_pk_bf16_f32 v18, v20, v21
	v_cvt_pk_bf16_f32 v19, v22, v23
	ds_write_b64 v109, v[18:19]
	v_cvt_pk_bf16_f32 v18, v24, v25
	v_cvt_pk_bf16_f32 v19, v26, v27
	ds_write_b64 v109, v[18:19] offset:4352
	v_cvt_pk_bf16_f32 v18, v28, v29
	v_cvt_pk_bf16_f32 v19, v30, v31
	ds_write_b64 v109, v[18:19] offset:8704
	v_cvt_pk_bf16_f32 v18, v32, v33
	v_cvt_pk_bf16_f32 v19, v34, v35
	ds_write_b64 v109, v[18:19] offset:13056
	s_waitcnt vmcnt(0) lgkmcnt(0)
	s_barrier
	ds_read_b64 v[220:221], v75
	ds_read_b64 v[222:223], v87
	ds_read_b64 v[224:225], v89
	ds_read_b64 v[226:227], v91
	ds_read_b64 v[228:229], v93
	ds_read_b64 v[230:231], v95
	ds_read_b64 v[232:233], v97
	ds_read_b64 v[234:235], v99
	v_lshlrev_b32_e32 v16, 16, v115
	v_lshlrev_b32_e32 v37, 16, v116
	v_lshlrev_b32_e32 v38, 16, v120
	v_lshlrev_b32_e32 v39, 16, v119
	s_waitcnt lgkmcnt(7)
	v_mul_f32_e32 v18, v220, v16
	v_mul_f32_e32 v19, v221, v37
	v_cvt_pk_bf16_f32 v36, v18, v19
	v_lshlrev_b32_e32 v43, 16, v122
	s_mov_b32 s22, 0xffff0000
	s_cmp_ge_i32 s69, s63
	s_waitcnt lgkmcnt(6)
	v_mul_f32_e32 v16, v222, v16
	v_mul_f32_e32 v18, v223, v37
	v_cvt_pk_bf16_f32 v40, v16, v18
	v_lshlrev_b32_e32 v16, 16, v117
	s_waitcnt lgkmcnt(5)
	v_mul_f32_e32 v18, v224, v16
	v_mul_f32_e32 v19, v225, v38
	v_cvt_pk_bf16_f32 v37, v18, v19
	s_waitcnt lgkmcnt(4)
	v_mul_f32_e32 v16, v226, v16
	v_mul_f32_e32 v18, v227, v38
	v_cvt_pk_bf16_f32 v41, v16, v18
	v_lshlrev_b32_e32 v16, 16, v118
	s_waitcnt lgkmcnt(3)
	v_mul_f32_e32 v18, v228, v16
	v_mul_f32_e32 v19, v229, v39
	v_cvt_pk_bf16_f32 v38, v18, v19
	s_waitcnt lgkmcnt(2)
	v_mul_f32_e32 v16, v230, v16
	v_mul_f32_e32 v18, v231, v39
	v_cvt_pk_bf16_f32 v42, v16, v18
	v_lshlrev_b32_e32 v16, 16, v121
	s_waitcnt lgkmcnt(1)
	v_mul_f32_e32 v18, v232, v16
	v_mul_f32_e32 v19, v233, v43
	v_cvt_pk_bf16_f32 v39, v18, v19
	s_waitcnt lgkmcnt(0)
	v_mul_f32_e32 v16, v234, v16
	v_mul_f32_e32 v18, v235, v43
	v_cvt_pk_bf16_f32 v43, v16, v18
	ds_write_b128 v79, v[36:39] offset:53248
	ds_write_b128 v79, v[40:43] offset:62464
	ds_read_b32 v236, v100 offset:17408
	ds_read_b32 v237, v101 offset:17680
	ds_read_b32 v238, v102 offset:17408
	ds_read_b32 v239, v103 offset:17680
	ds_read_b32 v240, v104 offset:17408
	ds_read_b32 v241, v105 offset:17680
	ds_read_b32 v242, v106 offset:17408
	ds_read_b32 v243, v107 offset:17680
	s_waitcnt lgkmcnt(7)
	v_and_b32_e32 v19, 0xffff, v236
	v_lshrrev_b32_e32 v16, 16, v236
	s_waitcnt lgkmcnt(6)
	v_lshl_or_b32 v36, v237, 16, v19
	v_and_or_b32 v40, v237, s22, v16
	s_waitcnt lgkmcnt(5)
	v_and_b32_e32 v19, 0xffff, v238
	v_lshrrev_b32_e32 v16, 16, v238
	s_waitcnt lgkmcnt(4)
	v_lshl_or_b32 v37, v239, 16, v19
	v_and_or_b32 v41, v239, s22, v16
	s_waitcnt lgkmcnt(3)
	v_and_b32_e32 v19, 0xffff, v240
	v_lshrrev_b32_e32 v16, 16, v240
	s_waitcnt lgkmcnt(2)
	v_lshl_or_b32 v38, v241, 16, v19
	v_and_or_b32 v42, v241, s22, v16
	s_waitcnt lgkmcnt(1)
	v_and_b32_e32 v19, 0xffff, v242
	s_waitcnt lgkmcnt(0)
	v_lshl_or_b32 v39, v243, 16, v19
	v_lshrrev_b32_e32 v16, 16, v242
	v_and_or_b32 v43, v243, s22, v16
	ds_write_b128 v80, v[36:39] offset:34816
	ds_write_b128 v80, v[40:43] offset:34960
	s_cbranch_scc1 .LBB0_356
	s_cmp_ge_i32 s80, s19
	s_mov_b64 s[74:75], -1
	s_cbranch_scc0 .LBB0_351
	s_sub_i32 s22, s80, s19
	s_mul_i32 s22, s22, s13
	s_add_i32 s76, s22, s62
	s_ashr_i32 s22, s76, 2
	s_and_b32 s22, s22, -8
	s_add_i32 s93, s22, 0x4080
	s_mov_b64 s[74:75], 0

; template <int DK, int DV, bool SEPQ> ...
;     ...
;     {
;         const float gi_i = GI[16 * m + fr];
;         const int n0 = 2 * hw, n1 = 2 * hw + 1; const bool do0 = n0 <= m, do1 = n1 <= m;
;         f32x4 acc0 = {0.f, 0.f, 0.f, 0.f}, acc1 = {0.f, 0.f, 0.f, 0.f};
; #pragma unroll
;         for (int vt = 0; vt < NVTW; ++vt) O[vt] = (f32x4){0.f, 0.f, 0.f, 0.f};
; #pragma unroll
;         for (int ks = 0; ks < DK / 32; ++ks) {
;             const bf16x8 qf = *(const bf16x8*)(QA + (16 * m + fr) * LQ + 32 * ks + 8 * fq);
;             if (do0) { const bf16x8 kf = *(const bf16x8*)(KB + (16 * n0 + fr) * LQ + 32 * ks + 8 * fq); acc0 = __builtin_amdgcn_mfma_f32_16x16x32_bf16(kf, qf, acc0, 0, 0, 0); }
;             if (do1) { const bf16x8 kf = *(const bf16x8*)(KB + (16 * n1 + fr) * LQ + 32 * ks + 8 * fq); acc1 = __builtin_amdgcn_mfma_f32_16x16x32_bf16(kf, qf, acc1, 0, 0, 0); }
;             bf16x8 qs = qf; if (SEPQ) qs = *(const bf16x8*)(QS + (16 * m + fr) * LQ + 32 * ks + 8 * fq);
; #pragma unroll
;             for (int vt = 0; vt < NVTW; ++vt) { const bf16x8 sf = *(const bf16x8*)(ST + (16 * (hw * NVTW + vt) + fr) * LQ + 32 * ks + 8 * fq); O[vt] = __builtin_amdgcn_mfma_f32_16x16x32_bf16(sf, qs, O[vt], 0, 0, 0); }
;         }
; #pragma unroll
;         for (int nn = 0; nn < 2; ++nn) {
;             const int n = 2 * hw + nn; const f32x4 acc = nn == 0 ? acc0 : acc1;
;             const f32x4 gj = *(const f32x4*)(GI + 16 * n + 4 * fq); const int i = 16 * m + fr, j0 = 16 * n + 4 * fq; float p[4];
; #pragma unroll
;             for (int e = 0; e < 4; ++e) p[e] = (j0 + e <= i) ? acc[e] * __expf(gi_i - gj[e]) : 0.f;
;             u32x2 w; w.x = cvt_pk_bf16(p[0], p[1]); w.y = cvt_pk_bf16(p[2], p[3]); *(u32x2*)(P + (16 * m + fr) * LJ + j0) = w;
;         }
;         const float ei = __expf(gi_i);
; #pragma unroll
;         for (int vt = 0; vt < NVTW; ++vt) O[vt] = O[vt] * ei;
;     }
;     __syncthreads();
; __device__ __forceinline__ void mamba_block(ArgsP a_, unsigned char* smem) { const ArgsP a = a_;
;     ...
;         if (i < len) { const float Dh = AIN(24)[hd];
; #pragma unroll
;             for (int vt = 0; vt < 2; ++vt) { const int v = 16 * (hw * 2 + vt) + 4 * fq; const size_t o = (size_t)(row0 + i) * 2048 + hd * 64 + v;
;                 const u32x2 xt = *(const u32x2*)(XC + (size_t)(row0 + i) * 4096 + hd * 64 + v); const u32x2 zt = *(const u32x2*)(ZG + o);
.LBB0_356:
	s_load_dwordx2 s[22:23], s[4:5], 0xc0
	v_add_u32_e32 v212, s72, v71
	v_ashrrev_i32_e32 v213, 31, v212
	v_lshlrev_b64 v[214:215], 11, v[212:213]
	v_lshlrev_b64 v[212:213], 13, v[212:213]
	v_readlane_b32 s74, v255, 12
	v_readlane_b32 s75, v255, 13
	v_lshl_or_b32 v216, s71, 6, v214
	v_or_b32_e32 v214, v216, v66
	s_nop 0
	v_lshl_add_u64 v[212:213], s[74:75], 0, v[212:213]
	s_lshl_b32 s74, s71, 7
	s_mov_b32 s75, s12
	v_lshl_add_u64 v[212:213], v[212:213], 0, s[74:75]
	v_lshlrev_b32_e32 v218, 1, v66
	v_mov_b32_e32 v219, 0
	v_lshl_add_u64 v[212:213], v[212:213], 0, v[218:219]
	v_lshlrev_b64 v[218:219], 1, v[214:215]
	global_load_dwordx2 v[202:203], v[212:213], off
	v_lshl_add_u64 v[218:219], s[24:25], 0, v[218:219]
	global_load_dwordx2 v[204:205], v[218:219], off
	global_load_dwordx2 v[206:207], v[212:213], off offset:32
	v_or_b32_e32 v214, v216, v68
	v_lshlrev_b64 v[218:219], 1, v[214:215]
	v_lshl_add_u64 v[218:219], s[24:25], 0, v[218:219]
	global_load_dwordx2 v[208:209], v[218:219], off
	s_lshl_b32 s74, s71, 2
	v_mov_b32_e32 v217, s74
	s_waitcnt lgkmcnt(0)
	global_load_dword v210, v217, s[22:23]
	s_waitcnt lgkmcnt(0)
	ds_read_b32 v123, v81
	ds_read_b128 v[220:223], v64
	ds_read_b128 v[224:227], v65 offset:17408
	ds_read_b128 v[228:231], v65 offset:21760
	ds_read_b128 v[232:235], v114
	ds_read_b128 v[236:239], v114 offset:4352
	ds_read_b128 v[164:167], v64 offset:64
	ds_read_b128 v[168:171], v65 offset:17472
	ds_read_b128 v[172:175], v65 offset:21824
	ds_read_b128 v[176:179], v114 offset:64
	ds_read_b128 v[180:183], v114 offset:4416
	s_waitcnt lgkmcnt(5)
	v_mfma_f32_16x16x32_bf16 v[40:43], v[224:227], v[220:223], 0
	v_mfma_f32_16x16x32_bf16 v[36:39], v[228:231], v[220:223], 0
	v_mfma_f32_16x16x32_bf16 v[44:47], v[232:235], v[220:223], 0
	v_mfma_f32_16x16x32_bf16 v[48:51], v[236:239], v[220:223], 0
	ds_read_b128 v[220:223], v64 offset:128
	ds_read_b128 v[224:227], v65 offset:17536
	ds_read_b128 v[228:231], v65 offset:21888
	ds_read_b128 v[232:235], v114 offset:128
	ds_read_b128 v[236:239], v114 offset:4480
	s_waitcnt lgkmcnt(5)
	v_mfma_f32_16x16x32_bf16 v[40:43], v[168:171], v[164:167], v[40:43]
	v_mfma_f32_16x16x32_bf16 v[36:39], v[172:175], v[164:167], v[36:39]
	v_mfma_f32_16x16x32_bf16 v[44:47], v[176:179], v[164:167], v[44:47]
	v_mfma_f32_16x16x32_bf16 v[48:51], v[180:183], v[164:167], v[48:51]
	ds_read_b128 v[164:167], v64 offset:192
	ds_read_b128 v[168:171], v65 offset:17600
	ds_read_b128 v[172:175], v65 offset:21952
	ds_read_b128 v[176:179], v114 offset:192
	ds_read_b128 v[180:183], v114 offset:4544
	s_waitcnt lgkmcnt(5)
	v_mfma_f32_16x16x32_bf16 v[40:43], v[224:227], v[220:223], v[40:43]
	v_mfma_f32_16x16x32_bf16 v[36:39], v[228:231], v[220:223], v[36:39]
	v_mfma_f32_16x16x32_bf16 v[44:47], v[232:235], v[220:223], v[44:47]
	v_mfma_f32_16x16x32_bf16 v[48:51], v[236:239], v[220:223], v[48:51]
	s_waitcnt lgkmcnt(0)
	v_mfma_f32_16x16x32_bf16 v[40:43], v[168:171], v[164:167], v[40:43]
	v_mfma_f32_16x16x32_bf16 v[36:39], v[172:175], v[164:167], v[36:39]
	v_mfma_f32_16x16x32_bf16 v[44:47], v[176:179], v[164:167], v[44:47]
	v_mfma_f32_16x16x32_bf16 v[48:51], v[180:183], v[164:167], v[48:51]
	s_nop 7
	v_cmp_gt_i32_e32 vcc, s73, v71
	ds_read_b128 v[52:55], v82
	s_waitcnt lgkmcnt(0)
	v_sub_f32_e32 v16, v123, v52
	v_mul_f32_e32 v16, 0x3fb8aa3b, v16
	v_exp_f32_e32 v16, v16
	v_sub_f32_e32 v18, v123, v53
	v_sub_f32_e32 v19, v123, v54
	v_mul_f32_e32 v18, 0x3fb8aa3b, v18
	v_mul_f32_e32 v16, v40, v16
	v_mul_f32_e32 v19, 0x3fb8aa3b, v19
	v_sub_f32_e32 v40, v123, v55
	v_exp_f32_e32 v18, v18
	v_exp_f32_e32 v19, v19
	v_mul_f32_e32 v40, 0x3fb8aa3b, v40
	v_exp_f32_e32 v40, v40
	v_mul_f32_e32 v18, v41, v18
	v_mul_f32_e32 v19, v42, v19
	v_cndmask_b32_e64 v18, 0, v18, s[48:49]
	v_cndmask_b32_e64 v19, v19, 0, s[50:51]
	v_mul_f32_e32 v40, v43, v40
	v_cndmask_b32_e64 v16, v16, 0, s[46:47]
	v_cndmask_b32_e64 v40, v40, 0, s[52:53]
	v_cvt_pk_bf16_f32 v18, v16, v18
	v_cvt_pk_bf16_f32 v19, v19, v40
	ds_write_b64 v83, v[18:19]
	ds_read_b128 v[40:43], v82 offset:64
	s_waitcnt lgkmcnt(0)
	v_sub_f32_e32 v16, v123, v40
	v_mul_f32_e32 v16, 0x3fb8aa3b, v16
	v_sub_f32_e32 v18, v123, v41
	v_exp_f32_e32 v16, v16
	v_mul_f32_e32 v18, 0x3fb8aa3b, v18
	v_exp_f32_e32 v18, v18
	v_sub_f32_e32 v19, v123, v42
	v_mul_f32_e32 v16, v36, v16
	v_sub_f32_e32 v36, v123, v43
	v_mul_f32_e32 v18, v37, v18
	v_mul_f32_e32 v19, 0x3fb8aa3b, v19
	v_mul_f32_e32 v36, 0x3fb8aa3b, v36
	v_cndmask_b32_e64 v16, v16, 0, s[54:55]
	v_cndmask_b32_e64 v18, 0, v18, s[56:57]
	v_exp_f32_e32 v19, v19
	v_exp_f32_e32 v36, v36
	v_cvt_pk_bf16_f32 v18, v16, v18
	v_mul_f32_e32 v16, 0x3fb8aa3b, v123
	v_exp_f32_e32 v16, v16
	v_mul_f32_e32 v19, v38, v19
	v_mul_f32_e32 v36, v39, v36
	v_cndmask_b32_e64 v19, v19, 0, s[58:59]
	v_cndmask_b32_e64 v36, v36, 0, s[60:61]
	v_cvt_pk_bf16_f32 v19, v19, v36
	ds_write_b64 v83, v[18:19] offset:32
	v_pk_mul_f32 v[36:37], v[16:17], v[44:45] op_sel_hi:[0,1]
	v_pk_mul_f32 v[38:39], v[16:17], v[46:47] op_sel_hi:[0,1]
	v_pk_mul_f32 v[40:41], v[16:17], v[48:49] op_sel_hi:[0,1]
	v_pk_mul_f32 v[42:43], v[16:17], v[50:51] op_sel_hi:[0,1]
	s_waitcnt lgkmcnt(0)
	s_barrier
; __device__ __forceinline__ unsigned cvt_pk_bf16(float lo, float hi) { unsigned r; asm("v_cvt_pk_bf16_f32 %0, %1, %2" : "=v"(r) : "v"(lo), "v"(hi)); return r; }
; template <int DK, int DV, bool SEPQ> ...
;     ...
; #pragma unroll
;     for (int ks = 0; ks < 2; ++ks) { const bf16x8 pf = *(const bf16x8*)(P + (16 * m + fr) * LJ + 32 * ks + 8 * fq);
; #pragma unroll
;         for (int vt = 0; vt < NVTW; ++vt) { const bf16x8 vf = *(const bf16x8*)(VT + (16 * (hw * NVTW + vt) + fr) * LJ + 32 * ks + 8 * fq); O[vt] = __builtin_amdgcn_mfma_f32_16x16x32_bf16(vf, pf, O[vt], 0, 0, 0); } }
; #pragma unroll
;     for (int ct = 0; ct < NCTW; ++ct) { const int ctg = wid * NCTW + ct; const f32x4 dec = *(const f32x4*)(SDEC + 16 * ctg + 4 * fq);
; #pragma unroll
;         for (int vt = 0; vt < NVT; ++vt) S[ct][vt] = S[ct][vt] * dec;
; #pragma unroll
;         for (int ks = 0; ks < 2; ++ks) { const bf16x8 kf = *(const bf16x8*)(KT + (16 * ctg + fr) * LJ + 32 * ks + 8 * fq);
; #pragma unroll
;             for (int vt = 0; vt < NVT; ++vt) { const bf16x8 vf = *(const bf16x8*)(VT2 + (16 * vt + fr) * LJ + 32 * ks + 8 * fq); S[ct][vt] = __builtin_amdgcn_mfma_f32_16x16x32_bf16(kf, vf, S[ct][vt], 0, 0, 0); } } }
; __device__ __forceinline__ void mamba_block(ArgsP a_, unsigned char* smem) { const ArgsP a = a_;
;     ...
;         const int m = wid >> 1, hw = wid & 1, i = 16 * m + fr;
;         if (i < len) { const float Dh = AIN(24)[hd];
; #pragma unroll
;             for (int vt = 0; vt < 2; ++vt) { const int v = 16 * (hw * 2 + vt) + 4 * fq; const size_t o = (size_t)(row0 + i) * 2048 + hd * 64 + v;
;                 const u32x2 xt = *(const u32x2*)(XC + (size_t)(row0 + i) * 4096 + hd * 64 + v); const u32x2 zt = *(const u32x2*)(ZG + o);
;                 const f32x4 xs = {__uint_as_float(xt.x << 16), __uint_as_float(xt.x & 0xffff0000u), __uint_as_float(xt.y << 16), __uint_as_float(xt.y & 0xffff0000u)};
;                 const f32x4 zg = {__uint_as_float(zt.x << 16), __uint_as_float(zt.x & 0xffff0000u), __uint_as_float(zt.y << 16), __uint_as_float(zt.y & 0xffff0000u)};
;                 const f32x4 y = (O[vt] + xs * Dh) * zg; *(u32x2*)(YB + o) = (u32x2){cvt_pk_bf16(y[0], y[1]), cvt_pk_bf16(y[2], y[3])}; } }
	ds_read_b128 v[220:223], v84
	ds_read_b128 v[224:227], v110 offset:53248
	ds_read_b128 v[228:231], v110 offset:55552
	ds_read_b128 v[232:235], v84 offset:64
	ds_read_b128 v[236:239], v110 offset:53312
	ds_read_b128 v[240:243], v110 offset:55616
	ds_read_b128 v[244:247], v111
	ds_read_b128 v[248:251], v70 offset:34816
	ds_read_b128 v[164:167], v112 offset:62464
	ds_read_b128 v[168:171], v112 offset:64768
	ds_read_b128 v[172:175], v113 offset:62464
	ds_read_b128 v[176:179], v113 offset:64768
	ds_read_b128 v[180:183], v70 offset:34880
	s_waitcnt lgkmcnt(11)
	v_mfma_f32_16x16x32_bf16 v[36:39], v[224:227], v[220:223], v[36:39]
	ds_read_b128 v[224:227], v112 offset:62528
	s_waitcnt lgkmcnt(11)
	v_mfma_f32_16x16x32_bf16 v[44:47], v[228:231], v[220:223], v[40:43]
	ds_read_b128 v[220:223], v112 offset:64832
	ds_read_b128 v[228:231], v113 offset:62528
	s_nop 1
	s_waitcnt lgkmcnt(11)
	v_mfma_f32_16x16x32_bf16 v[40:43], v[236:239], v[232:235], v[36:39]
	ds_read_b128 v[236:239], v113 offset:64832
	s_nop 2
	s_waitcnt lgkmcnt(11)
	v_mfma_f32_16x16x32_bf16 v[36:39], v[240:243], v[232:235], v[44:47]
	s_nop 2
	s_waitcnt lgkmcnt(10)
	v_pk_mul_f32 v[22:23], v[22:23], v[246:247]
	v_pk_mul_f32 v[20:21], v[20:21], v[244:245]
	v_pk_mul_f32 v[24:25], v[24:25], v[244:245]
	v_pk_mul_f32 v[26:27], v[26:27], v[246:247]
	v_pk_mul_f32 v[28:29], v[28:29], v[244:245]
	v_pk_mul_f32 v[30:31], v[30:31], v[246:247]
	v_pk_mul_f32 v[32:33], v[32:33], v[244:245]
	v_pk_mul_f32 v[34:35], v[34:35], v[246:247]
	s_waitcnt lgkmcnt(8)
	v_mfma_f32_16x16x32_bf16 v[18:21], v[248:251], v[164:167], v[20:23]
	s_waitcnt lgkmcnt(7)
	v_mfma_f32_16x16x32_bf16 v[24:27], v[248:251], v[168:171], v[24:27]
	s_waitcnt lgkmcnt(6)
	v_mfma_f32_16x16x32_bf16 v[28:31], v[248:251], v[172:175], v[28:31]
	s_waitcnt lgkmcnt(5)
	v_mfma_f32_16x16x32_bf16 v[32:35], v[248:251], v[176:179], v[32:35]
	s_waitcnt lgkmcnt(3)
	v_mfma_f32_16x16x32_bf16 v[20:23], v[180:183], v[224:227], v[18:21]
	s_waitcnt lgkmcnt(2)
	v_mfma_f32_16x16x32_bf16 v[24:27], v[180:183], v[220:223], v[24:27]
	s_waitcnt lgkmcnt(1)
	v_mfma_f32_16x16x32_bf16 v[28:31], v[180:183], v[228:231], v[28:31]
	s_waitcnt lgkmcnt(0)
	v_mfma_f32_16x16x32_bf16 v[32:35], v[180:183], v[236:239], v[32:35]
	s_and_saveexec_b64 s[74:75], vcc
	s_cbranch_execz .LBB0_374
	v_add_u32_e32 v44, s72, v71
	v_ashrrev_i32_e32 v45, 31, v44
	s_waitcnt vmcnt(0)
	v_mov_b32_e32 v18, v210
	v_readlane_b32 s22, v255, 12
	v_lshlrev_b64 v[46:47], 11, v[44:45]
	v_lshlrev_b64 v[44:45], 13, v[44:45]
	v_readlane_b32 s23, v255, 13
	v_lshl_or_b32 v19, s71, 6, v46
	v_or_b32_e32 v46, v19, v66
	v_lshl_add_u64 v[44:45], s[22:23], 0, v[44:45]
	s_lshl_b32 s22, s71, 7
	s_mov_b32 s23, s12
	v_lshl_add_u64 v[44:45], v[44:45], 0, s[22:23]
	v_lshlrev_b32_e32 v16, 1, v66
	v_lshl_add_u64 v[44:45], v[44:45], 0, v[16:17]
	v_lshlrev_b64 v[50:51], 1, v[46:47]
	v_mov_b32_e32 v48, v202
	v_mov_b32_e32 v49, v203
	v_lshl_add_u64 v[52:53], s[24:25], 0, v[50:51]
	v_mov_b32_e32 v52, v204
	v_mov_b32_e32 v53, v205
	v_or_b32_e32 v46, v19, v68
	v_lshlrev_b32_e32 v54, 16, v48
	v_and_b32_e32 v55, 0xffff0000, v48
	v_lshlrev_b32_e32 v48, 16, v49
	v_and_b32_e32 v49, 0xffff0000, v49
	v_lshlrev_b32_e32 v124, 16, v52
	v_and_b32_e32 v125, 0xffff0000, v52
	v_lshlrev_b32_e32 v52, 16, v53
	v_and_b32_e32 v53, 0xffff0000, v53
	v_pk_fma_f32 v[40:41], v[18:19], v[54:55], v[40:41] op_sel_hi:[0,1,1]
	v_pk_fma_f32 v[42:43], v[18:19], v[48:49], v[42:43] op_sel_hi:[0,1,1]
	v_pk_mul_f32 v[42:43], v[42:43], v[52:53]
	v_pk_mul_f32 v[40:41], v[40:41], v[124:125]
	s_nop 0
	v_cvt_pk_bf16_f32 v40, v40, v41
	v_cvt_pk_bf16_f32 v41, v42, v43
	v_lshl_add_u64 v[42:43], s[26:27], 0, v[50:51]
	global_store_dwordx2 v[42:43], v[40:41], off
	v_lshlrev_b64 v[42:43], 1, v[46:47]
	v_mov_b32_e32 v40, v206
	v_mov_b32_e32 v41, v207
	v_lshl_add_u64 v[44:45], s[24:25], 0, v[42:43]
	v_mov_b32_e32 v44, v208
	v_mov_b32_e32 v45, v209
	v_lshlrev_b32_e32 v46, 16, v40
	v_and_b32_e32 v47, 0xffff0000, v40
	v_lshlrev_b32_e32 v40, 16, v41
	v_and_b32_e32 v41, 0xffff0000, v41
	v_lshlrev_b32_e32 v48, 16, v44
	v_and_b32_e32 v49, 0xffff0000, v44
	v_lshlrev_b32_e32 v44, 16, v45
	v_and_b32_e32 v45, 0xffff0000, v45
	v_pk_fma_f32 v[36:37], v[18:19], v[46:47], v[36:37] op_sel_hi:[0,1,1]
	v_pk_fma_f32 v[18:19], v[18:19], v[40:41], v[38:39] op_sel_hi:[0,1,1]
	v_pk_mul_f32 v[18:19], v[18:19], v[44:45]
	v_pk_mul_f32 v[36:37], v[36:37], v[48:49]
	s_nop 0
	v_cvt_pk_bf16_f32 v36, v36, v37
	v_cvt_pk_bf16_f32 v37, v18, v19
	v_lshl_add_u64 v[18:19], s[26:27], 0, v[42:43]
	global_store_dwordx2 v[18:19], v[36:37], off
